# G2 (w_out) epilogue: the four gate loads are issued ahead of the K-loop into free VGPRs; epilogue waits vmcnt(6) instead of draining
# speedup vs baseline: 1.0141x; 1.0070x over previous
; #define PG8_STAGE(bufoff, gbase, voff) do { _Pragma("unroll") for (int _i = 0; _i < 2; ++_i) \
;         __builtin_amdgcn_global_load_lds((const unsigned*)((const char*)(gbase) + (voff)[_i]), (LAS unsigned*)(lds + (bufoff) + ldsw + _i * 8192), 16, 0, 0); } while (0)
; #define PG8_WAIT_V(n) asm volatile("s_waitcnt vmcnt(" #n ")" ::: "memory")
; template <class Epi>
; __device__ __forceinline__ void gemm_phase(LAS unsigned char* lds, const Gemm g, StaticOrder S, const Epi& E) {
;     ...
;     const char* cA = (const char*)g.A + (size_t)cur.pm * tstepA + (size_t)cur.pn * g.a_pn_off + (size_t)cur.kt0 * kstep; const char* cB = (const char*)g.Bt + (size_t)cur.pn * tstepB + (size_t)cur.kt0 * kstep;
;     PG8_STAGE(PG8_SB(0, 0), cB, voffB); PG8_STAGE(PG8_SA(0, 0), cA, voffA); PG8_STAGE(PG8_SB(0, 1), cB + hstepB, voffB); PG8_STAGE(PG8_SA(0, 1), cA + hstepA, voffA);
;     if (wr == 1) PG8_BAR;
;     PG8_WAIT_V(4); PG8_BAR;
;     PG8_STAGE(PG8_SB(1, 0), cB + kstep, voffB); PG8_STAGE(PG8_SA(1, 0), cA + kstep, voffA); PG8_STAGE(PG8_SB(1, 1), cB + hstepB + kstep, voffB);
;     PG8_WAIT_V(6); PG8_BAR;
;     for (;;) {
;         nxt = S.next(ui + 1); const bool has_next = nxt.nkt != 0;
;         const char* nA = has_next ? (const char*)g.A + (size_t)nxt.pm * tstepA + (size_t)nxt.pn * g.a_pn_off + (size_t)nxt.kt0 * kstep : cA; const char* nB = has_next ? (const char*)g.Bt + (size_t)nxt.pn * tstepB + (size_t)nxt.kt0 * kstep : cB;
;         const int ntc = cur.nkt;
;         for (int t = 0; t < ntc; t += 2) {
;             const bool last = (t == ntc - 2);
;             const char* a1 = cA + (size_t)(t + 1) * kstep;
;             const char* a2 = last ? nA : cA + (size_t)(t + 2) * kstep; const char* b2 = last ? nB : cB + (size_t)(t + 2) * kstep;
;             const char* a3 = a2 + kstep; const char* b3 = b2 + kstep;
;     __device__ __forceinline__ void operator()(const f32x4 (&acc)[2][2][4][2], const Unit& u, int wr, int wc, int fr, int fq) const {
;     ...
;         const int mr = u.pm < 64 ? (u.pm >> 4) : 4;
;         const float* gp = gate + (size_t)mr * 6 * D + col0;
;         f32x4 gv[2][2], bv[2][2];
; #pragma unroll
;         for (int bj = 0; bj < 2; ++bj)
; #pragma unroll
;             for (int n = 0; n < 2; ++n) { gv[bj][n] = *(const f32x4*)(gp + bj * 128 + 4 * n); bv[bj][n] = bias ? *(const f32x4*)(bias + col0 + bj * 128 + 4 * n) : (f32x4){0.f, 0.f, 0.f, 0.f}; }
.LBB0_692:
	s_cmp_eq_u32 s62, 0
	s_cselect_b64 s[18:19], -1, 0
	s_ashr_i32 s13, s12, 31
	s_lshl_b64 s[14:15], s[12:13], 20
	s_add_u32 s11, s41, s14
	s_addc_u32 s13, s42, s15
	s_add_u32 s14, s11, s20
	s_addc_u32 s15, s13, s21
	s_ashr_i32 s11, s10, 31
	s_lshl_b64 s[30:31], s[10:11], 20
	s_add_u32 s11, s43, s30
	s_addc_u32 s13, s44, s31
	s_add_u32 s20, s11, s20
	s_addc_u32 s21, s13, s21
	s_cmp_lt_i32 s63, 1
	s_cbranch_scc1 .LBB0_695
	s_and_b64 s[30:31], s[18:19], exec
	s_cselect_b32 s11, s27, s15
	s_cselect_b32 s13, s26, s14
	s_cselect_b32 s25, s29, s21
	s_cselect_b32 s65, s28, s20
	s_add_i32 s66, s63, -2
	s_add_u32 s26, s26, 0x80080
	s_addc_u32 s27, s27, 0
	s_add_u32 s67, s28, 0x100
	v_mov_b32_e32 v0, 0
	s_addc_u32 s70, s29, 0
	s_mov_b32 s28, 0
	v_mov_b32_e32 v1, v0
	v_mov_b32_e32 v2, v0
	v_mov_b32_e32 v3, v0
	v_mov_b32_e32 v4, v0
	v_mov_b32_e32 v5, v0
	v_mov_b32_e32 v6, v0
	v_mov_b32_e32 v7, v0
	v_mov_b32_e32 v16, v0
	v_mov_b32_e32 v17, v0
	v_mov_b32_e32 v18, v0
	v_mov_b32_e32 v19, v0
	v_mov_b32_e32 v20, v0
	v_mov_b32_e32 v21, v0
	v_mov_b32_e32 v22, v0
	v_mov_b32_e32 v23, v0
	v_mov_b32_e32 v32, v0
	v_mov_b32_e32 v33, v0
	v_mov_b32_e32 v34, v0
	v_mov_b32_e32 v35, v0
	v_mov_b32_e32 v36, v0
	v_mov_b32_e32 v37, v0
	v_mov_b32_e32 v38, v0
	v_mov_b32_e32 v39, v0
	v_mov_b32_e32 v48, v0
	v_mov_b32_e32 v49, v0
	v_mov_b32_e32 v50, v0
	v_mov_b32_e32 v51, v0
	v_mov_b32_e32 v52, v0
	v_mov_b32_e32 v53, v0
	v_mov_b32_e32 v54, v0
	v_mov_b32_e32 v55, v0
	v_mov_b32_e32 v8, v0
	v_mov_b32_e32 v9, v0
	v_mov_b32_e32 v10, v0
	v_mov_b32_e32 v11, v0
	v_mov_b32_e32 v12, v0
	v_mov_b32_e32 v13, v0
	v_mov_b32_e32 v14, v0
	v_mov_b32_e32 v15, v0
	v_mov_b32_e32 v24, v0
	v_mov_b32_e32 v25, v0
	v_mov_b32_e32 v26, v0
	v_mov_b32_e32 v27, v0
	v_mov_b32_e32 v28, v0
	v_mov_b32_e32 v29, v0
	v_mov_b32_e32 v30, v0
	v_mov_b32_e32 v31, v0
	v_mov_b32_e32 v40, v0
	v_mov_b32_e32 v41, v0
	v_mov_b32_e32 v42, v0
	v_mov_b32_e32 v43, v0
	v_mov_b32_e32 v44, v0
	v_mov_b32_e32 v45, v0
	v_mov_b32_e32 v46, v0
	v_mov_b32_e32 v47, v0
	v_mov_b32_e32 v56, v0
	v_mov_b32_e32 v57, v0
	v_mov_b32_e32 v58, v0
	v_mov_b32_e32 v59, v0
	v_mov_b32_e32 v60, v0
	v_mov_b32_e32 v61, v0
	v_mov_b32_e32 v62, v0
	v_mov_b32_e32 v63, v0
	v_mov_b32_e32 v66, v0
	v_mov_b32_e32 v67, v0
	v_mov_b32_e32 v68, v0
	v_mov_b32_e32 v69, v0
	v_mov_b32_e32 v70, v0
	v_mov_b32_e32 v71, v0
	v_mov_b32_e32 v72, v0
	v_mov_b32_e32 v73, v0
	v_mov_b32_e32 v82, v0
	v_mov_b32_e32 v83, v0
	v_mov_b32_e32 v84, v0
	v_mov_b32_e32 v85, v0
	v_mov_b32_e32 v86, v0
	v_mov_b32_e32 v87, v0
	v_mov_b32_e32 v88, v0
	v_mov_b32_e32 v89, v0
	v_mov_b32_e32 v98, v0
	v_mov_b32_e32 v99, v0
	v_mov_b32_e32 v100, v0
	v_mov_b32_e32 v101, v0
	v_mov_b32_e32 v102, v0
	v_mov_b32_e32 v103, v0
	v_mov_b32_e32 v104, v0
	v_mov_b32_e32 v105, v0
	v_mov_b32_e32 v114, v0
	v_mov_b32_e32 v115, v0
	v_mov_b32_e32 v116, v0
	v_mov_b32_e32 v117, v0
	v_mov_b32_e32 v118, v0
	v_mov_b32_e32 v119, v0
	v_mov_b32_e32 v120, v0
	v_mov_b32_e32 v121, v0
	v_mov_b32_e32 v74, v0
	v_mov_b32_e32 v75, v0
	v_mov_b32_e32 v76, v0
	v_mov_b32_e32 v77, v0
	v_mov_b32_e32 v78, v0
	v_mov_b32_e32 v79, v0
	v_mov_b32_e32 v80, v0
	v_mov_b32_e32 v81, v0
	v_mov_b32_e32 v90, v0
	v_mov_b32_e32 v91, v0
	v_mov_b32_e32 v92, v0
	v_mov_b32_e32 v93, v0
	v_mov_b32_e32 v94, v0
	v_mov_b32_e32 v95, v0
	v_mov_b32_e32 v96, v0
	v_mov_b32_e32 v97, v0
	v_mov_b32_e32 v106, v0
	v_mov_b32_e32 v107, v0
	v_mov_b32_e32 v108, v0
	v_mov_b32_e32 v109, v0
	v_mov_b32_e32 v110, v0
	v_mov_b32_e32 v111, v0
	v_mov_b32_e32 v112, v0
	v_mov_b32_e32 v113, v0
	v_mov_b32_e32 v122, v0
	v_mov_b32_e32 v123, v0
	v_mov_b32_e32 v124, v0
	v_mov_b32_e32 v125, v0
	v_mov_b32_e32 v126, v0
	v_mov_b32_e32 v127, v0
	v_mov_b32_e32 v128, v0
	v_mov_b32_e32 v129, v0
	s_ashr_i32 s98, s22, 4
	s_mul_i32 s98, s98, 6
	s_ashr_i32 s99, s98, 31
	s_lshl_b64 s[98:99], s[98:99], 11
	s_cmp_lt_i32 s22, 64
	s_cselect_b32 s99, s99, 0
	s_cselect_b32 s98, s98, 0xc000
	s_lshl_b64 s[98:99], s[98:99], 2
	s_add_u32 s98, s48, s98
	s_addc_u32 s99, s49, s99
	v_lshl_or_b32 v252, s24, 8, v176
	v_ashrrev_i32_e32 v253, 31, v252
	v_lshl_add_u64 v[252:253], v[252:253], 2, s[98:99]
	global_load_dwordx4 v[240:243], v[252:253], off
	global_load_dwordx4 v[244:247], v[252:253], off offset:16
	global_load_dwordx4 v[248:251], v[252:253], off offset:512
	global_load_dwordx4 v[252:255], v[252:253], off offset:528

; __device__ __forceinline__ unsigned pk2(float lo, float hi) { const v2f_t f = {lo, hi}; const v2bf_t b = __builtin_convertvector(f, v2bf_t); return __builtin_bit_cast(unsigned, b); }
; template <class Epi>
; __device__ __forceinline__ void gemm_phase(LAS unsigned char* lds, const Gemm g, StaticOrder S, const Epi& E) {
;     ...
; #pragma unroll
;         for (int a = 0; a < 2; ++a)
; #pragma unroll
;             for (int b = 0; b < 2; ++b)
; #pragma unroll
;                 for (int m = 0; m < 4; ++m)
; #pragma unroll
;                     for (int n = 0; n < 2; ++n) acc[a][b][m][n] = (f32x4){0.f, 0.f, 0.f, 0.f};
;     __device__ __forceinline__ void operator()(const f32x4 (&acc)[2][2][4][2], const Unit& u, int wr, int wc, int fr, int fq) const {
;         const int row0 = u.pm * 256 + wr * 64 + fr, col0 = u.pn * 256 + wc * 32 + 8 * fq;
;         if (u.part >= 0) {
;             float* pp = part + ((size_t)u.part * ROWS_CTX + (row0 - ROWS_LAT)) * D + col0;
; #pragma unroll
;             for (int ai = 0; ai < 2; ++ai)
; #pragma unroll
;                 for (int m = 0; m < 4; ++m)
; #pragma unroll
;                     for (int bj = 0; bj < 2; ++bj)
; #pragma unroll
;                         for (int n = 0; n < 2; ++n) *(f32x4*)(pp + (size_t)(ai * 128 + m * 16) * D + bj * 128 + 4 * n) = acc[ai][bj][m][n];
;             return;
;         }
;         const int mr = u.pm < 64 ? (u.pm >> 4) : 4;
;         const float* gp = gate + (size_t)mr * 6 * D + col0;
;         f32x4 gv[2][2], bv[2][2];
; #pragma unroll
;         for (int bj = 0; bj < 2; ++bj)
; #pragma unroll
;             for (int n = 0; n < 2; ++n) { gv[bj][n] = *(const f32x4*)(gp + bj * 128 + 4 * n); bv[bj][n] = bias ? *(const f32x4*)(bias + col0 + bj * 128 + 4 * n) : (f32x4){0.f, 0.f, 0.f, 0.f}; }
; #pragma unroll
;         for (int ai = 0; ai < 2; ++ai)
; #pragma unroll
;             for (int m = 0; m < 4; ++m) { bf16_t* rowp = delta + (size_t)(row0 + ai * 128 + m * 16) * D + col0;
; #pragma unroll
;                 for (int bj = 0; bj < 2; ++bj) { const f32x4 v0 = gv[bj][0] * (acc[ai][bj][m][0] + bv[bj][0]), v1 = gv[bj][1] * (acc[ai][bj][m][1] + bv[bj][1]);
;                     u32x4 w; w.x = pk2(v0[0], v0[1]); w.y = pk2(v0[2], v0[3]); w.z = pk2(v1[0], v1[1]); w.w = pk2(v1[2], v1[3]);
;                     *(u32x4*)(rowp + bj * 128) = w; } }
.LBB0_695:
	v_mov_b32_e32 v129, 0
	v_mov_b32_e32 v128, v129
	v_mov_b32_e32 v127, v129
	v_mov_b32_e32 v126, v129
	v_mov_b32_e32 v125, v129
	v_mov_b32_e32 v124, v129
	v_mov_b32_e32 v123, v129
	v_mov_b32_e32 v122, v129
	v_mov_b32_e32 v113, v129
	v_mov_b32_e32 v112, v129
	v_mov_b32_e32 v111, v129
	v_mov_b32_e32 v110, v129
	v_mov_b32_e32 v109, v129
	v_mov_b32_e32 v108, v129
	v_mov_b32_e32 v107, v129
	v_mov_b32_e32 v106, v129
	v_mov_b32_e32 v97, v129
	v_mov_b32_e32 v96, v129
	v_mov_b32_e32 v95, v129
	v_mov_b32_e32 v94, v129
	v_mov_b32_e32 v93, v129
	v_mov_b32_e32 v92, v129
	v_mov_b32_e32 v91, v129
	v_mov_b32_e32 v90, v129
	v_mov_b32_e32 v81, v129
	v_mov_b32_e32 v80, v129
	v_mov_b32_e32 v79, v129
	v_mov_b32_e32 v78, v129
	v_mov_b32_e32 v77, v129
	v_mov_b32_e32 v76, v129
	v_mov_b32_e32 v75, v129
	v_mov_b32_e32 v74, v129
	v_mov_b32_e32 v121, v129
	v_mov_b32_e32 v120, v129
	v_mov_b32_e32 v119, v129
	v_mov_b32_e32 v118, v129
	v_mov_b32_e32 v117, v129
	v_mov_b32_e32 v116, v129
	v_mov_b32_e32 v115, v129
	v_mov_b32_e32 v114, v129
	v_mov_b32_e32 v105, v129
	v_mov_b32_e32 v104, v129
	v_mov_b32_e32 v103, v129
	v_mov_b32_e32 v102, v129
	v_mov_b32_e32 v101, v129
	v_mov_b32_e32 v100, v129
	v_mov_b32_e32 v99, v129
	v_mov_b32_e32 v98, v129
	v_mov_b32_e32 v89, v129
	v_mov_b32_e32 v88, v129
	v_mov_b32_e32 v87, v129
	v_mov_b32_e32 v86, v129
	v_mov_b32_e32 v85, v129
	v_mov_b32_e32 v84, v129
	v_mov_b32_e32 v83, v129
	v_mov_b32_e32 v82, v129
	v_mov_b32_e32 v73, v129
	v_mov_b32_e32 v72, v129
	v_mov_b32_e32 v71, v129
	v_mov_b32_e32 v70, v129
	v_mov_b32_e32 v69, v129
	v_mov_b32_e32 v68, v129
	v_mov_b32_e32 v67, v129
	v_mov_b32_e32 v66, v129
	v_mov_b32_e32 v63, v129
	v_mov_b32_e32 v62, v129
	v_mov_b32_e32 v61, v129
	v_mov_b32_e32 v60, v129
	v_mov_b32_e32 v59, v129
	v_mov_b32_e32 v58, v129
	v_mov_b32_e32 v57, v129
	v_mov_b32_e32 v56, v129
	v_mov_b32_e32 v47, v129
	v_mov_b32_e32 v46, v129
	v_mov_b32_e32 v45, v129
	v_mov_b32_e32 v44, v129
	v_mov_b32_e32 v43, v129
	v_mov_b32_e32 v42, v129
	v_mov_b32_e32 v41, v129
	v_mov_b32_e32 v40, v129
	v_mov_b32_e32 v31, v129
	v_mov_b32_e32 v30, v129
	v_mov_b32_e32 v29, v129
	v_mov_b32_e32 v28, v129
	v_mov_b32_e32 v27, v129
	v_mov_b32_e32 v26, v129
	v_mov_b32_e32 v25, v129
	v_mov_b32_e32 v24, v129
	v_mov_b32_e32 v15, v129
	v_mov_b32_e32 v14, v129
	v_mov_b32_e32 v13, v129
	v_mov_b32_e32 v12, v129
	v_mov_b32_e32 v11, v129
	v_mov_b32_e32 v10, v129
	v_mov_b32_e32 v9, v129
	v_mov_b32_e32 v8, v129
	v_mov_b32_e32 v55, v129
	v_mov_b32_e32 v54, v129
	v_mov_b32_e32 v53, v129
	v_mov_b32_e32 v52, v129
	v_mov_b32_e32 v51, v129
	v_mov_b32_e32 v50, v129
	v_mov_b32_e32 v49, v129
	v_mov_b32_e32 v48, v129
	v_mov_b32_e32 v39, v129
	v_mov_b32_e32 v38, v129
	v_mov_b32_e32 v37, v129
	v_mov_b32_e32 v36, v129
	v_mov_b32_e32 v35, v129
	v_mov_b32_e32 v34, v129
	v_mov_b32_e32 v33, v129
	v_mov_b32_e32 v32, v129
	v_mov_b32_e32 v23, v129
	v_mov_b32_e32 v22, v129
	v_mov_b32_e32 v21, v129
	v_mov_b32_e32 v20, v129
	v_mov_b32_e32 v19, v129
	v_mov_b32_e32 v18, v129
	v_mov_b32_e32 v17, v129
	v_mov_b32_e32 v16, v129
	v_mov_b32_e32 v7, v129
	v_mov_b32_e32 v6, v129
	v_mov_b32_e32 v5, v129
	v_mov_b32_e32 v4, v129
	v_mov_b32_e32 v3, v129
	v_mov_b32_e32 v2, v129
	v_mov_b32_e32 v1, v129
	v_mov_b32_e32 v0, v129
	s_ashr_i32 s98, s22, 4
	s_mul_i32 s98, s98, 6
	s_ashr_i32 s99, s98, 31
	s_lshl_b64 s[98:99], s[98:99], 11
	s_cmp_lt_i32 s22, 64
	s_cselect_b32 s99, s99, 0
	s_cselect_b32 s98, s98, 0xc000
	s_lshl_b64 s[98:99], s[98:99], 2
	s_add_u32 s98, s48, s98
	s_addc_u32 s99, s49, s99
	v_lshl_or_b32 v252, s24, 8, v176
	v_ashrrev_i32_e32 v253, 31, v252
	v_lshl_add_u64 v[252:253], v[252:253], 2, s[98:99]
	global_load_dwordx4 v[240:243], v[252:253], off
	global_load_dwordx4 v[244:247], v[252:253], off offset:16
	global_load_dwordx4 v[248:251], v[252:253], off offset:512
	global_load_dwordx4 v[252:255], v[252:253], off offset:528
	s_waitcnt vmcnt(0)
.LBB0_696:
	v_lshl_or_b32 v156, s24, 8, v176
	v_lshl_add_u32 v158, s22, 8, v174
	s_cmp_lt_i32 s72, 0
	v_ashrrev_i32_e32 v157, 31, v156
	s_mov_b64 s[24:25], -1
	s_cbranch_scc0 .LBB0_698
	s_ashr_i32 s11, s22, 4
	s_mul_i32 s24, s11, 6
	s_ashr_i32 s25, s24, 31
	s_lshl_b64 s[24:25], s[24:25], 11
	s_cmp_lt_i32 s22, 64
	s_cselect_b32 s25, s25, 0
	s_cselect_b32 s24, s24, 0xc000
	s_lshl_b64 s[24:25], s[24:25], 2
	s_add_u32 s24, s48, s24
	s_addc_u32 s25, s49, s25
	v_and_b32_e32 v157, 15, v194
	v_bfe_u32 v170, v194, 6, 2
	v_bfe_u32 v171, v194, 4, 2
	v_bfe_u32 v172, v194, 8, 1
	v_lshlrev_b32_e32 v172, 4, v172
	v_add_u32_e32 v172, v172, v157
	v_mul_u32_u24_e32 v190, 0x110, v172
	v_lshl_add_u32 v190, v170, 6, v190
	v_lshl_add_u32 v190, v171, 4, v190
	v_add_u32_e32 v190, 0x23410, v190
	v_lshrrev_b32_e32 v172, 6, v194
	v_lshl_add_u32 v172, v172, 2, v171
	v_mul_u32_u24_e32 v191, 0x110, v172
	v_lshl_add_u32 v191, v157, 4, v191
	v_add_u32_e32 v191, 0x23410, v191
	v_sub_u32_e32 v172, v158, v157
	v_lshl_add_u32 v172, v170, 2, v172
	v_add_u32_e32 v172, v172, v171
	v_lshlrev_b32_e32 v172, 12, v172
	v_and_b32_e32 v173, 0xffffff00, v156
	v_lshlrev_b32_e32 v173, 1, v173
	v_lshl_add_u32 v173, v157, 4, v173
	v_add_u32_e32 v172, v172, v173
	v_mov_b32_e32 v173, 0
	v_lshl_add_u64 v[204:205], s[2:3], 0, v[172:173]
	s_mov_b32 s25, 0
	s_waitcnt vmcnt(6)
	v_pk_add_f32 v[126:127], v[126:127], 0 op_sel_hi:[1,0]
	v_pk_add_f32 v[128:129], v[128:129], 0 op_sel_hi:[1,0]
	v_pk_mul_f32 v[126:127], v[126:127], v[240:241]
	v_pk_mul_f32 v[128:129], v[128:129], v[242:243]
	v_pk_add_f32 v[122:123], v[122:123], 0 op_sel_hi:[1,0]
	v_pk_add_f32 v[124:125], v[124:125], 0 op_sel_hi:[1,0]
	v_pk_mul_f32 v[122:123], v[122:123], v[244:245]
	v_pk_mul_f32 v[124:125], v[124:125], v[246:247]
	v_cvt_pk_bf16_f32 v178, v126, v127
	v_cvt_pk_bf16_f32 v179, v128, v129
	v_cvt_pk_bf16_f32 v180, v122, v123
	v_cvt_pk_bf16_f32 v181, v124, v125
	ds_write_b128 v190, v[178:181]
	s_waitcnt lgkmcnt(0)
	s_barrier
; __device__ __forceinline__ unsigned pk2(float lo, float hi) { const v2f_t f = {lo, hi}; const v2bf_t b = __builtin_convertvector(f, v2bf_t); return __builtin_bit_cast(unsigned, b); }
;     __device__ __forceinline__ void operator()(const f32x4 (&acc)[2][2][4][2], const Unit& u, int wr, int wc, int fr, int fq) const {
;     ...
;         for (int ai = 0; ai < 2; ++ai)
; #pragma unroll
;             for (int m = 0; m < 4; ++m) { bf16_t* rowp = delta + (size_t)(row0 + ai * 128 + m * 16) * D + col0;
; #pragma unroll
;                 for (int bj = 0; bj < 2; ++bj) { const f32x4 v0 = gv[bj][0] * (acc[ai][bj][m][0] + bv[bj][0]), v1 = gv[bj][1] * (acc[ai][bj][m][1] + bv[bj][1]);
;                     u32x4 w; w.x = pk2(v0[0], v0[1]); w.y = pk2(v0[2], v0[3]); w.z = pk2(v1[0], v1[1]); w.w = pk2(v1[2], v1[3]);
;                     *(u32x4*)(rowp + bj * 128) = w; } }
	ds_read_b128 v[182:185], v191
	s_mov_b32 s24, 0x0
	v_lshl_add_u64 v[206:207], v[204:205], 0, s[24:25]
	v_pk_add_f32 v[118:119], v[118:119], 0 op_sel_hi:[1,0]
	v_pk_add_f32 v[120:121], v[120:121], 0 op_sel_hi:[1,0]
	v_pk_mul_f32 v[118:119], v[118:119], v[248:249]
	v_pk_mul_f32 v[120:121], v[120:121], v[250:251]
	v_pk_add_f32 v[114:115], v[114:115], 0 op_sel_hi:[1,0]
	v_pk_add_f32 v[116:117], v[116:117], 0 op_sel_hi:[1,0]
	v_pk_mul_f32 v[114:115], v[114:115], v[252:253]
	v_pk_mul_f32 v[116:117], v[116:117], v[254:255]
	v_cvt_pk_bf16_f32 v178, v118, v119
	v_cvt_pk_bf16_f32 v179, v120, v121
	v_cvt_pk_bf16_f32 v180, v114, v115
	v_cvt_pk_bf16_f32 v181, v116, v117
	ds_write_b128 v190, v[178:181] offset:8704
	s_waitcnt lgkmcnt(1)
	global_store_dwordx4 v[206:207], v[182:185], off
	s_waitcnt lgkmcnt(0)
	s_barrier
	ds_read_b128 v[186:189], v191 offset:8704
	v_pk_add_f32 v[110:111], v[110:111], 0 op_sel_hi:[1,0]
	v_pk_add_f32 v[112:113], v[112:113], 0 op_sel_hi:[1,0]
	v_pk_mul_f32 v[110:111], v[110:111], v[240:241]
	v_pk_mul_f32 v[112:113], v[112:113], v[242:243]
	v_pk_add_f32 v[106:107], v[106:107], 0 op_sel_hi:[1,0]
	v_pk_add_f32 v[108:109], v[108:109], 0 op_sel_hi:[1,0]
	v_pk_mul_f32 v[106:107], v[106:107], v[244:245]
	v_pk_mul_f32 v[108:109], v[108:109], v[246:247]
	v_cvt_pk_bf16_f32 v178, v110, v111
	v_cvt_pk_bf16_f32 v179, v112, v113
	v_cvt_pk_bf16_f32 v180, v106, v107
	v_cvt_pk_bf16_f32 v181, v108, v109
	ds_write_b128 v190, v[178:181]
	s_waitcnt lgkmcnt(1)
	global_store_dwordx4 v[206:207], v[186:189], off offset:256
	s_waitcnt lgkmcnt(0)
	s_barrier
	ds_read_b128 v[182:185], v191
	s_mov_b32 s24, 0x10000
	v_lshl_add_u64 v[206:207], v[204:205], 0, s[24:25]
	v_pk_add_f32 v[102:103], v[102:103], 0 op_sel_hi:[1,0]
	v_pk_add_f32 v[104:105], v[104:105], 0 op_sel_hi:[1,0]
	v_pk_mul_f32 v[102:103], v[102:103], v[248:249]
	v_pk_mul_f32 v[104:105], v[104:105], v[250:251]
	v_pk_add_f32 v[98:99], v[98:99], 0 op_sel_hi:[1,0]
	v_pk_add_f32 v[100:101], v[100:101], 0 op_sel_hi:[1,0]
	v_pk_mul_f32 v[98:99], v[98:99], v[252:253]
	v_pk_mul_f32 v[100:101], v[100:101], v[254:255]
	v_cvt_pk_bf16_f32 v178, v102, v103
	v_cvt_pk_bf16_f32 v179, v104, v105
	v_cvt_pk_bf16_f32 v180, v98, v99
	v_cvt_pk_bf16_f32 v181, v100, v101
	ds_write_b128 v190, v[178:181] offset:8704
	s_waitcnt lgkmcnt(1)
	global_store_dwordx4 v[206:207], v[182:185], off
	s_waitcnt lgkmcnt(0)
	s_barrier
	ds_read_b128 v[186:189], v191 offset:8704
	v_pk_add_f32 v[94:95], v[94:95], 0 op_sel_hi:[1,0]
	v_pk_add_f32 v[96:97], v[96:97], 0 op_sel_hi:[1,0]
	v_pk_mul_f32 v[94:95], v[94:95], v[240:241]
	v_pk_mul_f32 v[96:97], v[96:97], v[242:243]
	v_pk_add_f32 v[90:91], v[90:91], 0 op_sel_hi:[1,0]
	v_pk_add_f32 v[92:93], v[92:93], 0 op_sel_hi:[1,0]
	v_pk_mul_f32 v[90:91], v[90:91], v[244:245]
	v_pk_mul_f32 v[92:93], v[92:93], v[246:247]
	v_cvt_pk_bf16_f32 v178, v94, v95
	v_cvt_pk_bf16_f32 v179, v96, v97
	v_cvt_pk_bf16_f32 v180, v90, v91
	v_cvt_pk_bf16_f32 v181, v92, v93
	ds_write_b128 v190, v[178:181]
	s_waitcnt lgkmcnt(1)
	global_store_dwordx4 v[206:207], v[186:189], off offset:256
	s_waitcnt lgkmcnt(0)
	s_barrier
	ds_read_b128 v[182:185], v191
	s_mov_b32 s24, 0x20000
	v_lshl_add_u64 v[206:207], v[204:205], 0, s[24:25]
	v_pk_add_f32 v[86:87], v[86:87], 0 op_sel_hi:[1,0]
	v_pk_add_f32 v[88:89], v[88:89], 0 op_sel_hi:[1,0]
	v_pk_mul_f32 v[86:87], v[86:87], v[248:249]
	v_pk_mul_f32 v[88:89], v[88:89], v[250:251]
	v_pk_add_f32 v[82:83], v[82:83], 0 op_sel_hi:[1,0]
	v_pk_add_f32 v[84:85], v[84:85], 0 op_sel_hi:[1,0]
	v_pk_mul_f32 v[82:83], v[82:83], v[252:253]
	v_pk_mul_f32 v[84:85], v[84:85], v[254:255]
	v_cvt_pk_bf16_f32 v178, v86, v87
	v_cvt_pk_bf16_f32 v179, v88, v89
	v_cvt_pk_bf16_f32 v180, v82, v83
	v_cvt_pk_bf16_f32 v181, v84, v85
	ds_write_b128 v190, v[178:181] offset:8704
	s_waitcnt lgkmcnt(1)
	global_store_dwordx4 v[206:207], v[182:185], off
	s_waitcnt lgkmcnt(0)
	s_barrier
	ds_read_b128 v[186:189], v191 offset:8704
	v_pk_add_f32 v[78:79], v[78:79], 0 op_sel_hi:[1,0]
	v_pk_add_f32 v[80:81], v[80:81], 0 op_sel_hi:[1,0]
	v_pk_mul_f32 v[78:79], v[78:79], v[240:241]
	v_pk_mul_f32 v[80:81], v[80:81], v[242:243]
	v_pk_add_f32 v[74:75], v[74:75], 0 op_sel_hi:[1,0]
	v_pk_add_f32 v[76:77], v[76:77], 0 op_sel_hi:[1,0]
	v_pk_mul_f32 v[74:75], v[74:75], v[244:245]
	v_pk_mul_f32 v[76:77], v[76:77], v[246:247]
	v_cvt_pk_bf16_f32 v178, v78, v79
	v_cvt_pk_bf16_f32 v179, v80, v81
	v_cvt_pk_bf16_f32 v180, v74, v75
	v_cvt_pk_bf16_f32 v181, v76, v77
	ds_write_b128 v190, v[178:181]
	s_waitcnt lgkmcnt(1)
	global_store_dwordx4 v[206:207], v[186:189], off offset:256
	s_waitcnt lgkmcnt(0)
	s_barrier
	ds_read_b128 v[182:185], v191
	s_mov_b32 s24, 0x30000
	v_lshl_add_u64 v[206:207], v[204:205], 0, s[24:25]
	v_pk_add_f32 v[70:71], v[70:71], 0 op_sel_hi:[1,0]
	v_pk_add_f32 v[72:73], v[72:73], 0 op_sel_hi:[1,0]
	v_pk_mul_f32 v[70:71], v[70:71], v[248:249]
	v_pk_mul_f32 v[72:73], v[72:73], v[250:251]
	v_pk_add_f32 v[66:67], v[66:67], 0 op_sel_hi:[1,0]
	v_pk_add_f32 v[68:69], v[68:69], 0 op_sel_hi:[1,0]
	v_pk_mul_f32 v[66:67], v[66:67], v[252:253]
	v_pk_mul_f32 v[68:69], v[68:69], v[254:255]
	v_cvt_pk_bf16_f32 v178, v70, v71
	v_cvt_pk_bf16_f32 v179, v72, v73
	v_cvt_pk_bf16_f32 v180, v66, v67
	v_cvt_pk_bf16_f32 v181, v68, v69
	ds_write_b128 v190, v[178:181] offset:8704
	s_waitcnt lgkmcnt(1)
	global_store_dwordx4 v[206:207], v[182:185], off
	s_waitcnt lgkmcnt(0)
	s_barrier
; __device__ __forceinline__ unsigned pk2(float lo, float hi) { const v2f_t f = {lo, hi}; const v2bf_t b = __builtin_convertvector(f, v2bf_t); return __builtin_bit_cast(unsigned, b); }
;     __device__ __forceinline__ void operator()(const f32x4 (&acc)[2][2][4][2], const Unit& u, int wr, int wc, int fr, int fq) const {
;     ...
;         for (int ai = 0; ai < 2; ++ai)
; #pragma unroll
;             for (int m = 0; m < 4; ++m) { bf16_t* rowp = delta + (size_t)(row0 + ai * 128 + m * 16) * D + col0;
; #pragma unroll
;                 for (int bj = 0; bj < 2; ++bj) { const f32x4 v0 = gv[bj][0] * (acc[ai][bj][m][0] + bv[bj][0]), v1 = gv[bj][1] * (acc[ai][bj][m][1] + bv[bj][1]);
;                     u32x4 w; w.x = pk2(v0[0], v0[1]); w.y = pk2(v0[2], v0[3]); w.z = pk2(v1[0], v1[1]); w.w = pk2(v1[2], v1[3]);
;                     *(u32x4*)(rowp + bj * 128) = w; } }
	ds_read_b128 v[186:189], v191 offset:8704
	v_pk_add_f32 v[60:61], v[60:61], 0 op_sel_hi:[1,0]
	v_pk_add_f32 v[62:63], v[62:63], 0 op_sel_hi:[1,0]
	v_pk_mul_f32 v[60:61], v[60:61], v[240:241]
	v_pk_mul_f32 v[62:63], v[62:63], v[242:243]
	v_pk_add_f32 v[56:57], v[56:57], 0 op_sel_hi:[1,0]
	v_pk_add_f32 v[58:59], v[58:59], 0 op_sel_hi:[1,0]
	v_pk_mul_f32 v[56:57], v[56:57], v[244:245]
	v_pk_mul_f32 v[58:59], v[58:59], v[246:247]
	v_cvt_pk_bf16_f32 v178, v60, v61
	v_cvt_pk_bf16_f32 v179, v62, v63
	v_cvt_pk_bf16_f32 v180, v56, v57
	v_cvt_pk_bf16_f32 v181, v58, v59
	ds_write_b128 v190, v[178:181]
	s_waitcnt lgkmcnt(1)
	global_store_dwordx4 v[206:207], v[186:189], off offset:256
	s_waitcnt lgkmcnt(0)
	s_barrier
	ds_read_b128 v[182:185], v191
	s_mov_b32 s24, 0x80000
	v_lshl_add_u64 v[206:207], v[204:205], 0, s[24:25]
	v_pk_add_f32 v[52:53], v[52:53], 0 op_sel_hi:[1,0]
	v_pk_add_f32 v[54:55], v[54:55], 0 op_sel_hi:[1,0]
	v_pk_mul_f32 v[52:53], v[52:53], v[248:249]
	v_pk_mul_f32 v[54:55], v[54:55], v[250:251]
	v_pk_add_f32 v[48:49], v[48:49], 0 op_sel_hi:[1,0]
	v_pk_add_f32 v[50:51], v[50:51], 0 op_sel_hi:[1,0]
	v_pk_mul_f32 v[48:49], v[48:49], v[252:253]
	v_pk_mul_f32 v[50:51], v[50:51], v[254:255]
	v_cvt_pk_bf16_f32 v178, v52, v53
	v_cvt_pk_bf16_f32 v179, v54, v55
	v_cvt_pk_bf16_f32 v180, v48, v49
	v_cvt_pk_bf16_f32 v181, v50, v51
	ds_write_b128 v190, v[178:181] offset:8704
	s_waitcnt lgkmcnt(1)
	global_store_dwordx4 v[206:207], v[182:185], off
	s_waitcnt lgkmcnt(0)
	s_barrier
	ds_read_b128 v[186:189], v191 offset:8704
	v_pk_add_f32 v[44:45], v[44:45], 0 op_sel_hi:[1,0]
	v_pk_add_f32 v[46:47], v[46:47], 0 op_sel_hi:[1,0]
	v_pk_mul_f32 v[44:45], v[44:45], v[240:241]
	v_pk_mul_f32 v[46:47], v[46:47], v[242:243]
	v_pk_add_f32 v[40:41], v[40:41], 0 op_sel_hi:[1,0]
	v_pk_add_f32 v[42:43], v[42:43], 0 op_sel_hi:[1,0]
	v_pk_mul_f32 v[40:41], v[40:41], v[244:245]
	v_pk_mul_f32 v[42:43], v[42:43], v[246:247]
	v_cvt_pk_bf16_f32 v178, v44, v45
	v_cvt_pk_bf16_f32 v179, v46, v47
	v_cvt_pk_bf16_f32 v180, v40, v41
	v_cvt_pk_bf16_f32 v181, v42, v43
	ds_write_b128 v190, v[178:181]
	s_waitcnt lgkmcnt(1)
	global_store_dwordx4 v[206:207], v[186:189], off offset:256
	s_waitcnt lgkmcnt(0)
	s_barrier
	ds_read_b128 v[182:185], v191
	s_mov_b32 s24, 0x90000
	v_lshl_add_u64 v[206:207], v[204:205], 0, s[24:25]
	v_pk_add_f32 v[36:37], v[36:37], 0 op_sel_hi:[1,0]
	v_pk_add_f32 v[38:39], v[38:39], 0 op_sel_hi:[1,0]
	v_pk_mul_f32 v[36:37], v[36:37], v[248:249]
	v_pk_mul_f32 v[38:39], v[38:39], v[250:251]
	v_pk_add_f32 v[32:33], v[32:33], 0 op_sel_hi:[1,0]
	v_pk_add_f32 v[34:35], v[34:35], 0 op_sel_hi:[1,0]
	v_pk_mul_f32 v[32:33], v[32:33], v[252:253]
	v_pk_mul_f32 v[34:35], v[34:35], v[254:255]
	v_cvt_pk_bf16_f32 v178, v36, v37
	v_cvt_pk_bf16_f32 v179, v38, v39
	v_cvt_pk_bf16_f32 v180, v32, v33
	v_cvt_pk_bf16_f32 v181, v34, v35
	ds_write_b128 v190, v[178:181] offset:8704
	s_waitcnt lgkmcnt(1)
	global_store_dwordx4 v[206:207], v[182:185], off
	s_waitcnt lgkmcnt(0)
	s_barrier
	ds_read_b128 v[186:189], v191 offset:8704
	v_pk_add_f32 v[28:29], v[28:29], 0 op_sel_hi:[1,0]
	v_pk_add_f32 v[30:31], v[30:31], 0 op_sel_hi:[1,0]
	v_pk_mul_f32 v[28:29], v[28:29], v[240:241]
	v_pk_mul_f32 v[30:31], v[30:31], v[242:243]
	v_pk_add_f32 v[24:25], v[24:25], 0 op_sel_hi:[1,0]
	v_pk_add_f32 v[26:27], v[26:27], 0 op_sel_hi:[1,0]
	v_pk_mul_f32 v[24:25], v[24:25], v[244:245]
	v_pk_mul_f32 v[26:27], v[26:27], v[246:247]
	v_cvt_pk_bf16_f32 v178, v28, v29
	v_cvt_pk_bf16_f32 v179, v30, v31
	v_cvt_pk_bf16_f32 v180, v24, v25
	v_cvt_pk_bf16_f32 v181, v26, v27
	ds_write_b128 v190, v[178:181]
	s_waitcnt lgkmcnt(1)
	global_store_dwordx4 v[206:207], v[186:189], off offset:256
	s_waitcnt lgkmcnt(0)
	s_barrier
	ds_read_b128 v[182:185], v191
	s_mov_b32 s24, 0xa0000
	v_lshl_add_u64 v[206:207], v[204:205], 0, s[24:25]
	v_pk_add_f32 v[20:21], v[20:21], 0 op_sel_hi:[1,0]
	v_pk_add_f32 v[22:23], v[22:23], 0 op_sel_hi:[1,0]
	v_pk_mul_f32 v[20:21], v[20:21], v[248:249]
	v_pk_mul_f32 v[22:23], v[22:23], v[250:251]
	v_pk_add_f32 v[16:17], v[16:17], 0 op_sel_hi:[1,0]
	v_pk_add_f32 v[18:19], v[18:19], 0 op_sel_hi:[1,0]
	v_pk_mul_f32 v[16:17], v[16:17], v[252:253]
	v_pk_mul_f32 v[18:19], v[18:19], v[254:255]
	v_cvt_pk_bf16_f32 v178, v20, v21
	v_cvt_pk_bf16_f32 v179, v22, v23
	v_cvt_pk_bf16_f32 v180, v16, v17
	v_cvt_pk_bf16_f32 v181, v18, v19
	ds_write_b128 v190, v[178:181] offset:8704
	s_waitcnt lgkmcnt(1)
	global_store_dwordx4 v[206:207], v[182:185], off
	s_waitcnt lgkmcnt(0)
	s_barrier
	ds_read_b128 v[186:189], v191 offset:8704
	v_pk_add_f32 v[12:13], v[12:13], 0 op_sel_hi:[1,0]
	v_pk_add_f32 v[14:15], v[14:15], 0 op_sel_hi:[1,0]
	v_pk_mul_f32 v[12:13], v[12:13], v[240:241]
	v_pk_mul_f32 v[14:15], v[14:15], v[242:243]
	v_pk_add_f32 v[8:9], v[8:9], 0 op_sel_hi:[1,0]
	v_pk_add_f32 v[10:11], v[10:11], 0 op_sel_hi:[1,0]
	v_pk_mul_f32 v[8:9], v[8:9], v[244:245]
	v_pk_mul_f32 v[10:11], v[10:11], v[246:247]
	v_cvt_pk_bf16_f32 v178, v12, v13
	v_cvt_pk_bf16_f32 v179, v14, v15
	v_cvt_pk_bf16_f32 v180, v8, v9
	v_cvt_pk_bf16_f32 v181, v10, v11
	ds_write_b128 v190, v[178:181]
	s_waitcnt lgkmcnt(1)
	global_store_dwordx4 v[206:207], v[186:189], off offset:256
	s_waitcnt lgkmcnt(0)
	s_barrier
	ds_read_b128 v[182:185], v191
	s_mov_b32 s24, 0xb0000
	v_lshl_add_u64 v[206:207], v[204:205], 0, s[24:25]
	v_pk_add_f32 v[4:5], v[4:5], 0 op_sel_hi:[1,0]
	v_pk_add_f32 v[6:7], v[6:7], 0 op_sel_hi:[1,0]
	v_pk_mul_f32 v[4:5], v[4:5], v[248:249]
	v_pk_mul_f32 v[6:7], v[6:7], v[250:251]
	v_pk_add_f32 v[0:1], v[0:1], 0 op_sel_hi:[1,0]
	v_pk_add_f32 v[2:3], v[2:3], 0 op_sel_hi:[1,0]
	v_pk_mul_f32 v[0:1], v[0:1], v[252:253]
	v_pk_mul_f32 v[2:3], v[2:3], v[254:255]
	v_cvt_pk_bf16_f32 v178, v4, v5
	v_cvt_pk_bf16_f32 v179, v6, v7
	v_cvt_pk_bf16_f32 v180, v0, v1
	v_cvt_pk_bf16_f32 v181, v2, v3
	ds_write_b128 v190, v[178:181] offset:8704
	s_waitcnt lgkmcnt(1)
	global_store_dwordx4 v[206:207], v[182:185], off
	s_waitcnt lgkmcnt(0)
	s_barrier
	ds_read_b128 v[186:189], v191 offset:8704
	s_waitcnt lgkmcnt(0)
	global_store_dwordx4 v[206:207], v[186:189], off offset:256
	s_mov_b64 s[24:25], 0
